# P0 conv_mat and prep_rows f32 input loads marked nt (read-once streaming data, no cache pollution)
# speedup vs baseline: 1.0095x; 1.0095x over previous
; #define LAS __attribute__((address_space(3)))
; __device__ __forceinline__ void tr_item(const float* W, const float* nw, int K, int N, bf16* WT, int k0, int n0, int drow0, LAS float* scr, int lane) {
;     { const int r = lane >> 3, c4 = lane & 7; f32x4 v[8];
; #pragma unroll
;       for (int i = 0; i < 8; ++i) v[i] = *(const f32x4*)(W + (size_t)(k0 + 8 * i + r) * N + n0 + 4 * c4);
; #pragma unroll
;       for (int i = 0; i < 8; ++i) { LAS float* d = scr + (8 * i + r) * 33 + 4 * c4; const float s = nw ? nw[k0 + 8 * i + r] : 1.f; d[0] = v[i].x * s; d[1] = v[i].y * s; d[2] = v[i].z * s; d[3] = v[i].w * s; } }
; template <int MODE> __device__ __forceinline__ void conv_mat(const float* W, const float* nw, int K, int N, bf16* WT, LAS float* scr, int gw, int NGW, int lane) {
;     const int nblk = N / 32, nitems = (K / 64) * nblk;
;     for (int it = gw; it < nitems; it += NGW) { const int kb = it / nblk, nb = it % nblk, n0 = 32 * nb; int d = n0;
;         if (MODE == 1) { d = (n0 < DFF) ? 256 * (n0 / 128) + (n0 % 128) : 256 * ((n0 - DFF) / 128) + 128 + ((n0 - DFF) % 128); }
;         tr_item(W, nw, K, N, WT, 64 * kb, n0, d, scr, lane); }
.LBB0_25:
	s_lshl_b32 s8, s11, 6
	v_or_b32_e32 v40, s8, v224
	s_ashr_i32 s11, s10, 31
	v_lshl_add_u64 v[2:3], s[10:11], 2, v[36:37]
	v_or_b32_e32 v6, 8, v40
	v_mad_i64_i32 v[4:5], s[10:11], v40, s21, v[2:3]
	v_mad_i64_i32 v[6:7], s[10:11], v6, s21, v[2:3]
	global_load_dwordx4 v[30:33], v[4:5], off nt
	global_load_dwordx4 v[26:29], v[6:7], off nt
	v_or_b32_e32 v4, 16, v40
	v_or_b32_e32 v6, 24, v40
	v_mad_i64_i32 v[4:5], s[10:11], v4, s21, v[2:3]
	v_mad_i64_i32 v[6:7], s[10:11], v6, s21, v[2:3]
	global_load_dwordx4 v[22:25], v[4:5], off nt
	global_load_dwordx4 v[18:21], v[6:7], off nt
	v_or_b32_e32 v4, 32, v40
	v_or_b32_e32 v6, 40, v40
	v_mad_i64_i32 v[4:5], s[10:11], v4, s21, v[2:3]
	v_mad_i64_i32 v[6:7], s[10:11], v6, s21, v[2:3]
	global_load_dwordx4 v[14:17], v[4:5], off nt
	global_load_dwordx4 v[10:13], v[6:7], off nt
	v_or_b32_e32 v4, 48, v40
	v_or_b32_e32 v6, 56, v40
	v_mad_i64_i32 v[4:5], s[10:11], v4, s21, v[2:3]
	v_mad_i64_i32 v[2:3], s[10:11], v6, s21, v[2:3]
	global_load_dwordx4 v[6:9], v[4:5], off nt
	s_nop 0
	global_load_dwordx4 v[2:5], v[2:3], off nt
	v_ashrrev_i32_e32 v41, 31, v40
	v_lshl_add_u64 v[40:41], v[40:41], 2, s[18:19]
	global_load_dword v245, v[40:41], off
	global_load_dword v246, v[40:41], off offset:32
	global_load_dword v247, v[40:41], off offset:64
	global_load_dword v248, v[40:41], off offset:96
	global_load_dword v249, v[40:41], off offset:128
	global_load_dword v251, v[40:41], off offset:160
	global_load_dword v252, v[40:41], off offset:192
	global_load_dword v253, v[40:41], off offset:224
	s_waitcnt vmcnt(0)
	v_mul_f32_e32 v30, v245, v30
	v_mul_f32_e32 v31, v245, v31
	v_mul_f32_e32 v32, v245, v32
	v_mul_f32_e32 v33, v245, v33
	v_mul_f32_e32 v26, v246, v26
	v_mul_f32_e32 v27, v246, v27
	v_mul_f32_e32 v28, v246, v28
	v_mul_f32_e32 v29, v246, v29
	v_mul_f32_e32 v22, v247, v22
	v_mul_f32_e32 v23, v247, v23
	v_mul_f32_e32 v24, v247, v24
	v_mul_f32_e32 v25, v247, v25
	v_mul_f32_e32 v18, v248, v18
	v_mul_f32_e32 v19, v248, v19
	v_mul_f32_e32 v20, v248, v20
	v_mul_f32_e32 v21, v248, v21
	v_mul_f32_e32 v14, v249, v14
	v_mul_f32_e32 v15, v249, v15
	v_mul_f32_e32 v16, v249, v16
	v_mul_f32_e32 v17, v249, v17
	v_mul_f32_e32 v10, v251, v10
	v_mul_f32_e32 v11, v251, v11
	v_mul_f32_e32 v12, v251, v12
	v_mul_f32_e32 v13, v251, v13
	v_mul_f32_e32 v6, v252, v6
	v_mul_f32_e32 v7, v252, v7
	v_mul_f32_e32 v8, v252, v8
	v_mul_f32_e32 v9, v252, v9
	v_mul_f32_e32 v2, v253, v2
	v_mul_f32_e32 v3, v253, v3
	v_mul_f32_e32 v4, v253, v4
	v_mul_f32_e32 v5, v253, v5
	ds_write2_b32 v46, v30, v31 offset1:1
	ds_write2_b32 v46, v32, v33 offset0:2 offset1:3
	v_add_u32_e32 v254, 0x420, v46
	ds_write2_b32 v254, v26, v27 offset1:1
	ds_write2_b32 v254, v28, v29 offset0:2 offset1:3
	v_add_u32_e32 v254, 0x840, v46
	ds_write2_b32 v254, v22, v23 offset1:1
	ds_write2_b32 v254, v24, v25 offset0:2 offset1:3
	v_add_u32_e32 v254, 0xc60, v46
	ds_write2_b32 v254, v18, v19 offset1:1
	ds_write2_b32 v254, v20, v21 offset0:2 offset1:3
	v_add_u32_e32 v254, 0x1080, v46
	ds_write2_b32 v254, v14, v15 offset1:1
	ds_write2_b32 v254, v16, v17 offset0:2 offset1:3
	v_add_u32_e32 v254, 0x14a0, v46
	ds_write2_b32 v254, v10, v11 offset1:1
	ds_write2_b32 v254, v12, v13 offset0:2 offset1:3
	v_add_u32_e32 v254, 0x18c0, v46
	ds_write2_b32 v254, v6, v7 offset1:1
	ds_write2_b32 v254, v8, v9 offset0:2 offset1:3
	v_add_u32_e32 v254, 0x1ce0, v46
	ds_write2_b32 v254, v2, v3 offset1:1
	ds_write2_b32 v254, v4, v5 offset0:2 offset1:3
	s_branch .LBB0_20

; #define LAS __attribute__((address_space(3)))
; __device__ __forceinline__ unsigned pkbf(float lo, float hi) { const f32x2_m v = {lo, hi}; const bf16x2_m b = __builtin_convertvector(v, bf16x2_m); return __builtin_bit_cast(unsigned, b); }
; __device__ __forceinline__ void tr_item(const float* W, const float* nw, int K, int N, bf16* WT, int k0, int n0, int drow0, LAS float* scr, int lane) {
;     { const int r = lane >> 3, c4 = lane & 7; f32x4 v[8];
; #pragma unroll
;       for (int i = 0; i < 8; ++i) v[i] = *(const f32x4*)(W + (size_t)(k0 + 8 * i + r) * N + n0 + 4 * c4);
; #pragma unroll
;       for (int i = 0; i < 8; ++i) { LAS float* d = scr + (8 * i + r) * 33 + 4 * c4; const float s = nw ? nw[k0 + 8 * i + r] : 1.f; d[0] = v[i].x * s; d[1] = v[i].y * s; d[2] = v[i].z * s; d[3] = v[i].w * s; } }
;     asm volatile("s_waitcnt lgkmcnt(0)" ::: "memory");
;     const int c = lane & 7;
; #pragma unroll
;     for (int j = 0; j < 4; ++j) { const int n = (lane >> 3) + 8 * j; const LAS float* s = scr + (8 * c) * 33 + n;
;         v4u o; o.x = pkbf(s[0 * 33], s[1 * 33]); o.y = pkbf(s[2 * 33], s[3 * 33]); o.z = pkbf(s[4 * 33], s[5 * 33]); o.w = pkbf(s[6 * 33], s[7 * 33]);
;         *(v4u*)(WT + (size_t)(drow0 + n) * K + k0 + 8 * c) = o; }
;     asm volatile("s_waitcnt lgkmcnt(0)" ::: "memory");
; }
; template <int MODE> __device__ __forceinline__ void conv_mat(const float* W, const float* nw, int K, int N, bf16* WT, LAS float* scr, int gw, int NGW, int lane) {
;     const int nblk = N / 32, nitems = (K / 64) * nblk;
;     for (int it = gw; it < nitems; it += NGW) { const int kb = it / nblk, nb = it % nblk, n0 = 32 * nb; int d = n0;
;         if (MODE == 1) { d = (n0 < DFF) ? 256 * (n0 / 128) + (n0 % 128) : 256 * ((n0 - DFF) / 128) + 128 + ((n0 - DFF) % 128); }
;         tr_item(W, nw, K, N, WT, 64 * kb, n0, d, scr, lane); }
.LBB0_35:
	s_ashr_i32 s4, s9, 31
	s_lshr_b32 s4, s4, 26
	s_add_i32 s4, s9, s4
	s_ashr_i32 s10, s4, 6
	s_andn2_b32 s4, s4, 63
	s_lshl_b32 s5, s10, 11
	v_or_b32_e32 v22, s4, v224
	s_sub_i32 s14, s3, s5
	v_ashrrev_i32_e32 v23, 31, v22
	v_or_b32_e32 v24, 8, v22
	v_or_b32_e32 v26, 16, v22
	v_or_b32_e32 v28, 24, v22
	v_or_b32_e32 v30, 32, v22
	v_or_b32_e32 v32, 40, v22
	v_or_b32_e32 v36, 48, v22
	v_or_b32_e32 v38, 56, v22
	s_ashr_i32 s15, s14, 31
	v_lshlrev_b64 v[22:23], 13, v[22:23]
	v_ashrrev_i32_e32 v25, 31, v24
	v_ashrrev_i32_e32 v27, 31, v26
	v_ashrrev_i32_e32 v29, 31, v28
	v_ashrrev_i32_e32 v31, 31, v30
	v_ashrrev_i32_e32 v33, 31, v32
	v_ashrrev_i32_e32 v37, 31, v36
	v_ashrrev_i32_e32 v39, 31, v38
	v_lshl_add_u64 v[40:41], s[14:15], 2, v[2:3]
	v_lshlrev_b64 v[24:25], 13, v[24:25]
	v_lshlrev_b64 v[26:27], 13, v[26:27]
	v_lshlrev_b64 v[28:29], 13, v[28:29]
	v_lshlrev_b64 v[30:31], 13, v[30:31]
	v_lshlrev_b64 v[32:33], 13, v[32:33]
	v_lshlrev_b64 v[36:37], 13, v[36:37]
	v_lshlrev_b64 v[38:39], 13, v[38:39]
	v_lshl_add_u64 v[56:57], v[40:41], 0, v[22:23]
	v_lshl_add_u64 v[58:59], v[40:41], 0, v[24:25]
	v_lshl_add_u64 v[60:61], v[40:41], 0, v[26:27]
	v_lshl_add_u64 v[62:63], v[40:41], 0, v[28:29]
	v_lshl_add_u64 v[64:65], v[40:41], 0, v[30:31]
	v_lshl_add_u64 v[66:67], v[40:41], 0, v[32:33]
	v_lshl_add_u64 v[68:69], v[40:41], 0, v[36:37]
	v_lshl_add_u64 v[70:71], v[40:41], 0, v[38:39]
	global_load_dwordx4 v[22:25], v[56:57], off nt
	global_load_dwordx4 v[26:29], v[58:59], off nt
	global_load_dwordx4 v[30:33], v[60:61], off nt
	global_load_dwordx4 v[36:39], v[62:63], off nt
	global_load_dwordx4 v[40:43], v[64:65], off nt
	global_load_dwordx4 v[44:47], v[66:67], off nt
	global_load_dwordx4 v[48:51], v[68:69], off nt
	global_load_dwordx4 v[52:55], v[70:71], off nt
	s_mul_i32 s10, s10, 0xff500000
	v_add_u32_e32 v58, s10, v6
	s_ashr_i32 s5, s4, 31
	v_add_u32_e32 v60, 0xb000, v58
	v_add_u32_e32 v62, 0x16000, v58
	v_add_u32_e32 v64, 0x21000, v58
	v_lshl_add_u64 v[56:57], s[4:5], 1, v[4:5]
	v_ashrrev_i32_e32 v59, 31, v58
	v_ashrrev_i32_e32 v61, 31, v60
	v_ashrrev_i32_e32 v63, 31, v62
	v_ashrrev_i32_e32 v65, 31, v64
	v_lshl_add_u64 v[58:59], v[58:59], 1, v[56:57]
	v_lshl_add_u64 v[60:61], v[60:61], 1, v[56:57]
	v_lshl_add_u64 v[62:63], v[62:63], 1, v[56:57]
	v_lshl_add_u64 v[56:57], v[64:65], 1, v[56:57]
	s_add_i32 s9, s9, s64
	s_add_i32 s3, s3, s8
	s_cmpk_lt_i32 s9, 0x1600
	v_add_u32_e32 v6, s11, v6
	s_waitcnt vmcnt(7)
	ds_write2_b32 v7, v22, v23 offset1:1
	ds_write2_b32 v7, v24, v25 offset0:2 offset1:3
	s_waitcnt vmcnt(6)
	ds_write2_b32 v8, v26, v27 offset1:1
	ds_write2_b32 v9, v28, v29 offset1:1
	s_waitcnt vmcnt(5)
	ds_write2_b32 v10, v30, v31 offset1:1
	ds_write2_b32 v11, v32, v33 offset1:1
	s_waitcnt vmcnt(4)
	ds_write2_b32 v12, v36, v37 offset1:1
	ds_write2_b32 v13, v38, v39 offset1:1
	s_waitcnt vmcnt(3)
	ds_write2_b32 v14, v40, v41 offset1:1
	ds_write2_b32 v15, v42, v43 offset1:1
	s_waitcnt vmcnt(2)
	ds_write2_b32 v16, v44, v45 offset1:1
	ds_write2_b32 v17, v46, v47 offset1:1
	s_waitcnt vmcnt(1)
	ds_write2_b32 v18, v48, v49 offset1:1
	ds_write2_b32 v19, v50, v51 offset1:1
	s_waitcnt vmcnt(0)
	ds_write2_b32 v20, v52, v53 offset1:1
	ds_write2_b32 v21, v54, v55 offset1:1
	s_waitcnt lgkmcnt(0)
	ds_read2_b32 v[24:25], v1 offset0:33 offset1:41
	ds_read2_b32 v[26:27], v1 offset1:8
	ds_read2_b32 v[28:29], v1 offset0:66 offset1:74
	ds_read2_b32 v[30:31], v1 offset0:99 offset1:107
	ds_read2_b32 v[32:33], v1 offset0:132 offset1:140
	ds_read2_b32 v[36:37], v1 offset0:165 offset1:173
	ds_read2_b32 v[38:39], v1 offset0:198 offset1:206
	ds_read2_b32 v[40:41], v1 offset0:231 offset1:239
	ds_read2_b32 v[42:43], v1 offset0:49 offset1:57
	ds_read2_b32 v[44:45], v1 offset0:16 offset1:24
	ds_read2_b32 v[46:47], v1 offset0:82 offset1:90
	ds_read2_b32 v[48:49], v1 offset0:115 offset1:123
	ds_read2_b32 v[50:51], v1 offset0:148 offset1:156
	ds_read2_b32 v[52:53], v1 offset0:181 offset1:189
	ds_read2_b32 v[54:55], v1 offset0:214 offset1:222
	ds_read2_b32 v[64:65], v1 offset0:247 offset1:255
	s_waitcnt lgkmcnt(14)
	v_cvt_pk_bf16_f32 v22, v26, v24
	s_waitcnt lgkmcnt(12)
	v_cvt_pk_bf16_f32 v23, v28, v30
	v_cvt_pk_bf16_f32 v26, v27, v25
	s_waitcnt lgkmcnt(10)
	v_cvt_pk_bf16_f32 v24, v32, v36
	s_waitcnt lgkmcnt(8)
	v_cvt_pk_bf16_f32 v25, v38, v40
	v_cvt_pk_bf16_f32 v27, v29, v31
	v_cvt_pk_bf16_f32 v28, v33, v37
	v_cvt_pk_bf16_f32 v29, v39, v41
	s_waitcnt lgkmcnt(6)
	v_cvt_pk_bf16_f32 v30, v44, v42
	s_waitcnt lgkmcnt(4)
	v_cvt_pk_bf16_f32 v31, v46, v48
	s_waitcnt lgkmcnt(2)
	v_cvt_pk_bf16_f32 v32, v50, v52
	s_waitcnt lgkmcnt(0)
	v_cvt_pk_bf16_f32 v33, v54, v64
	v_cvt_pk_bf16_f32 v36, v45, v43
	v_cvt_pk_bf16_f32 v37, v47, v49
	v_cvt_pk_bf16_f32 v38, v51, v53
	v_cvt_pk_bf16_f32 v39, v55, v65
	global_store_dwordx4 v[58:59], v[22:25], off
	global_store_dwordx4 v[60:61], v[26:29], off
	global_store_dwordx4 v[62:63], v[30:33], off
	global_store_dwordx4 v[56:57], v[36:39], off
	s_waitcnt lgkmcnt(0)
	s_cbranch_scc1 .LBB0_35

; #define LAS __attribute__((address_space(3)))
; __device__ __forceinline__ void tr_item(const float* W, const float* nw, int K, int N, bf16* WT, int k0, int n0, int drow0, LAS float* scr, int lane) {
;     { const int r = lane >> 3, c4 = lane & 7; f32x4 v[8];
; #pragma unroll
;       for (int i = 0; i < 8; ++i) v[i] = *(const f32x4*)(W + (size_t)(k0 + 8 * i + r) * N + n0 + 4 * c4);
; #pragma unroll
;       for (int i = 0; i < 8; ++i) { LAS float* d = scr + (8 * i + r) * 33 + 4 * c4; const float s = nw ? nw[k0 + 8 * i + r] : 1.f; d[0] = v[i].x * s; d[1] = v[i].y * s; d[2] = v[i].z * s; d[3] = v[i].w * s; } }
; template <int MODE> __device__ __forceinline__ void conv_mat(const float* W, const float* nw, int K, int N, bf16* WT, LAS float* scr, int gw, int NGW, int lane) {
;     const int nblk = N / 32, nitems = (K / 64) * nblk;
;     for (int it = gw; it < nitems; it += NGW) { const int kb = it / nblk, nb = it % nblk, n0 = 32 * nb; int d = n0;
;         if (MODE == 1) { d = (n0 < DFF) ? 256 * (n0 / 128) + (n0 % 128) : 256 * ((n0 - DFF) / 128) + 128 + ((n0 - DFF) % 128); }
;         tr_item(W, nw, K, N, WT, 64 * kb, n0, d, scr, lane); }
.LBB0_39:
	s_mul_hi_i32 s4, s14, 0x2e8ba2e9
	s_lshr_b32 s5, s4, 31
	s_ashr_i32 s4, s4, 6
	s_add_i32 s5, s4, s5
	s_mul_i32 s4, s5, 0xffffd400
	s_add_i32 s4, s3, s4
	s_lshl_b32 s8, s5, 6
	v_or_b32_e32 v40, s8, v224
	s_ashr_i32 s5, s4, 31
	v_lshl_add_u64 v[2:3], s[4:5], 2, v[36:37]
	v_or_b32_e32 v6, 8, v40
	v_mad_i64_i32 v[4:5], s[20:21], v40, s11, v[2:3]
	v_mad_i64_i32 v[6:7], s[20:21], v6, s11, v[2:3]
	global_load_dwordx4 v[30:33], v[4:5], off nt
	global_load_dwordx4 v[26:29], v[6:7], off nt
	v_or_b32_e32 v4, 16, v40
	v_or_b32_e32 v6, 24, v40
	v_mad_i64_i32 v[4:5], s[20:21], v4, s11, v[2:3]
	v_mad_i64_i32 v[6:7], s[20:21], v6, s11, v[2:3]
	global_load_dwordx4 v[22:25], v[4:5], off nt
	global_load_dwordx4 v[18:21], v[6:7], off nt
	v_or_b32_e32 v4, 32, v40
	v_or_b32_e32 v6, 40, v40
	v_mad_i64_i32 v[4:5], s[20:21], v4, s11, v[2:3]
	v_mad_i64_i32 v[6:7], s[20:21], v6, s11, v[2:3]
	global_load_dwordx4 v[14:17], v[4:5], off nt
	global_load_dwordx4 v[10:13], v[6:7], off nt
	v_or_b32_e32 v4, 48, v40
	v_or_b32_e32 v6, 56, v40
	v_mad_i64_i32 v[4:5], s[20:21], v4, s11, v[2:3]
	v_mad_i64_i32 v[2:3], s[20:21], v6, s11, v[2:3]
	global_load_dwordx4 v[6:9], v[4:5], off nt
	s_nop 0
	global_load_dwordx4 v[2:5], v[2:3], off nt
	v_ashrrev_i32_e32 v41, 31, v40
	v_lshl_add_u64 v[40:41], v[40:41], 2, s[24:25]
	global_load_dword v245, v[40:41], off
	global_load_dword v246, v[40:41], off offset:32
	global_load_dword v247, v[40:41], off offset:64
	global_load_dword v248, v[40:41], off offset:96
	global_load_dword v249, v[40:41], off offset:128
	global_load_dword v251, v[40:41], off offset:160
	global_load_dword v252, v[40:41], off offset:192
	global_load_dword v253, v[40:41], off offset:224
	s_waitcnt vmcnt(0)
	v_mul_f32_e32 v30, v245, v30
	v_mul_f32_e32 v31, v245, v31
	v_mul_f32_e32 v32, v245, v32
	v_mul_f32_e32 v33, v245, v33
	v_mul_f32_e32 v26, v246, v26
	v_mul_f32_e32 v27, v246, v27
	v_mul_f32_e32 v28, v246, v28
	v_mul_f32_e32 v29, v246, v29
	v_mul_f32_e32 v22, v247, v22
	v_mul_f32_e32 v23, v247, v23
	v_mul_f32_e32 v24, v247, v24
	v_mul_f32_e32 v25, v247, v25
	v_mul_f32_e32 v18, v248, v18
	v_mul_f32_e32 v19, v248, v19
	v_mul_f32_e32 v20, v248, v20
	v_mul_f32_e32 v21, v248, v21
	v_mul_f32_e32 v14, v249, v14
	v_mul_f32_e32 v15, v249, v15
	v_mul_f32_e32 v16, v249, v16
	v_mul_f32_e32 v17, v249, v17
	v_mul_f32_e32 v10, v251, v10
	v_mul_f32_e32 v11, v251, v11
	v_mul_f32_e32 v12, v251, v12
	v_mul_f32_e32 v13, v251, v13
	v_mul_f32_e32 v6, v252, v6
	v_mul_f32_e32 v7, v252, v7
	v_mul_f32_e32 v8, v252, v8
	v_mul_f32_e32 v9, v252, v9
	v_mul_f32_e32 v2, v253, v2
	v_mul_f32_e32 v3, v253, v3
	v_mul_f32_e32 v4, v253, v4
	v_mul_f32_e32 v5, v253, v5
	ds_write2_b32 v35, v30, v31 offset1:1
	ds_write2_b32 v35, v32, v33 offset0:2 offset1:3
	v_add_u32_e32 v254, 0x420, v35
	ds_write2_b32 v254, v26, v27 offset1:1
	ds_write2_b32 v254, v28, v29 offset0:2 offset1:3
	v_add_u32_e32 v254, 0x840, v35
	ds_write2_b32 v254, v22, v23 offset1:1
	ds_write2_b32 v254, v24, v25 offset0:2 offset1:3
	v_add_u32_e32 v254, 0xc60, v35
	ds_write2_b32 v254, v18, v19 offset1:1
	ds_write2_b32 v254, v20, v21 offset0:2 offset1:3
	v_add_u32_e32 v254, 0x1080, v35
	ds_write2_b32 v254, v14, v15 offset1:1
	ds_write2_b32 v254, v16, v17 offset0:2 offset1:3
	v_add_u32_e32 v254, 0x14a0, v35
	ds_write2_b32 v254, v10, v11 offset1:1
	ds_write2_b32 v254, v12, v13 offset0:2 offset1:3
	v_add_u32_e32 v254, 0x18c0, v35
	ds_write2_b32 v254, v6, v7 offset1:1
	ds_write2_b32 v254, v8, v9 offset0:2 offset1:3
	v_add_u32_e32 v254, 0x1ce0, v35
	ds_write2_b32 v254, v2, v3 offset1:1
	ds_write2_b32 v254, v4, v5 offset0:2 offset1:3
	s_branch .LBB0_38

; #define LAS __attribute__((address_space(3)))
; __device__ __forceinline__ unsigned pkbf(float lo, float hi) { const f32x2_m v = {lo, hi}; const bf16x2_m b = __builtin_convertvector(v, bf16x2_m); return __builtin_bit_cast(unsigned, b); }
; __device__ __forceinline__ void tr_item(const float* W, const float* nw, int K, int N, bf16* WT, int k0, int n0, int drow0, LAS float* scr, int lane) {
;     { const int r = lane >> 3, c4 = lane & 7; f32x4 v[8];
; #pragma unroll
;       for (int i = 0; i < 8; ++i) v[i] = *(const f32x4*)(W + (size_t)(k0 + 8 * i + r) * N + n0 + 4 * c4);
; #pragma unroll
;       for (int i = 0; i < 8; ++i) { LAS float* d = scr + (8 * i + r) * 33 + 4 * c4; const float s = nw ? nw[k0 + 8 * i + r] : 1.f; d[0] = v[i].x * s; d[1] = v[i].y * s; d[2] = v[i].z * s; d[3] = v[i].w * s; } }
;     asm volatile("s_waitcnt lgkmcnt(0)" ::: "memory");
;     const int c = lane & 7;
; #pragma unroll
;     for (int j = 0; j < 4; ++j) { const int n = (lane >> 3) + 8 * j; const LAS float* s = scr + (8 * c) * 33 + n;
;         v4u o; o.x = pkbf(s[0 * 33], s[1 * 33]); o.y = pkbf(s[2 * 33], s[3 * 33]); o.z = pkbf(s[4 * 33], s[5 * 33]); o.w = pkbf(s[6 * 33], s[7 * 33]);
;         *(v4u*)(WT + (size_t)(drow0 + n) * K + k0 + 8 * c) = o; }
;     asm volatile("s_waitcnt lgkmcnt(0)" ::: "memory");
; }
; template <int MODE> __device__ __forceinline__ void conv_mat(const float* W, const float* nw, int K, int N, bf16* WT, LAS float* scr, int gw, int NGW, int lane) {
;     const int nblk = N / 32, nitems = (K / 64) * nblk;
;     for (int it = gw; it < nitems; it += NGW) { const int kb = it / nblk, nb = it % nblk, n0 = 32 * nb; int d = n0;
;         if (MODE == 1) { d = (n0 < DFF) ? 256 * (n0 / 128) + (n0 % 128) : 256 * ((n0 - DFF) / 128) + 128 + ((n0 - DFF) % 128); }
;         tr_item(W, nw, K, N, WT, 64 * kb, n0, d, scr, lane); }
.LBB0_49:
	s_ashr_i32 s0, s8, 31
	s_lshr_b32 s0, s0, 26
	s_add_i32 s0, s8, s0
	s_lshl_b32 s1, s0, 5
	s_andn2_b32 s0, s0, 63
	s_and_b32 s1, s1, 0xfffff800
	v_or_b32_e32 v24, s0, v224
	s_sub_i32 s4, s7, s1
	v_or_b32_e32 v26, 8, v24
	v_or_b32_e32 v28, 16, v24
	v_or_b32_e32 v30, 24, v24
	v_or_b32_e32 v36, 40, v24
	v_or_b32_e32 v38, 48, v24
	v_or_b32_e32 v40, 56, v24
	v_ashrrev_i32_e32 v25, 31, v24
	v_or_b32_e32 v32, 32, v24
	s_ashr_i32 s5, s4, 31
	v_ashrrev_i32_e32 v27, 31, v26
	v_ashrrev_i32_e32 v29, 31, v28
	v_ashrrev_i32_e32 v31, 31, v30
	v_ashrrev_i32_e32 v37, 31, v36
	v_ashrrev_i32_e32 v39, 31, v38
	v_ashrrev_i32_e32 v41, 31, v40
	v_lshlrev_b64 v[24:25], 13, v[24:25]
	v_ashrrev_i32_e32 v33, 31, v32
	v_lshl_add_u64 v[42:43], s[4:5], 2, v[6:7]
	v_lshlrev_b64 v[26:27], 13, v[26:27]
	v_lshlrev_b64 v[28:29], 13, v[28:29]
	v_lshlrev_b64 v[30:31], 13, v[30:31]
	v_lshlrev_b64 v[36:37], 13, v[36:37]
	v_lshlrev_b64 v[38:39], 13, v[38:39]
	v_lshlrev_b64 v[40:41], 13, v[40:41]
	v_lshlrev_b64 v[32:33], 13, v[32:33]
	v_lshl_add_u64 v[24:25], v[42:43], 0, v[24:25]
	v_lshl_add_u64 v[44:45], v[42:43], 0, v[26:27]
	v_lshl_add_u64 v[46:47], v[42:43], 0, v[28:29]
	v_lshl_add_u64 v[48:49], v[42:43], 0, v[30:31]
	v_lshl_add_u64 v[50:51], v[42:43], 0, v[36:37]
	v_lshl_add_u64 v[52:53], v[42:43], 0, v[38:39]
	v_lshl_add_u64 v[56:57], v[42:43], 0, v[40:41]
	v_lshl_add_u64 v[32:33], v[42:43], 0, v[32:33]
	global_load_dwordx4 v[24:27], v[24:25], off nt
	s_nop 0
	global_load_dwordx4 v[28:31], v[44:45], off nt
	global_load_dwordx4 v[36:39], v[46:47], off nt
	global_load_dwordx4 v[40:43], v[48:49], off nt
	s_nop 0
	global_load_dwordx4 v[44:47], v[32:33], off nt
	s_nop 0
	global_load_dwordx4 v[48:51], v[50:51], off nt
	s_nop 0
	global_load_dwordx4 v[52:55], v[52:53], off nt
	s_nop 0
	global_load_dwordx4 v[56:59], v[56:57], off nt
	v_add_u32_e32 v60, s4, v224
	v_add_u32_e32 v62, 8, v60
	v_add_u32_e32 v64, 16, v60
	v_add_u32_e32 v66, 24, v60
	s_ashr_i32 s1, s0, 31
	v_ashrrev_i32_e32 v61, 31, v60
	v_ashrrev_i32_e32 v63, 31, v62
	v_ashrrev_i32_e32 v65, 31, v64
	v_ashrrev_i32_e32 v67, 31, v66
	v_lshl_add_u64 v[32:33], s[0:1], 1, v[8:9]
	v_lshlrev_b64 v[60:61], 11, v[60:61]
	v_lshlrev_b64 v[62:63], 11, v[62:63]
	v_lshlrev_b64 v[64:65], 11, v[64:65]
	v_lshlrev_b64 v[66:67], 11, v[66:67]
	v_lshl_add_u64 v[60:61], v[32:33], 0, v[60:61]
	v_lshl_add_u64 v[62:63], v[32:33], 0, v[62:63]
	v_lshl_add_u64 v[64:65], v[32:33], 0, v[64:65]
	v_lshl_add_u64 v[32:33], v[32:33], 0, v[66:67]
	s_add_i32 s8, s8, s64
	s_add_i32 s7, s7, s6
	s_cmpk_lt_i32 s8, 0x400
	s_waitcnt vmcnt(7)
	ds_write2_b32 v10, v24, v25 offset1:1
	ds_write2_b32 v10, v26, v27 offset0:2 offset1:3
	s_waitcnt vmcnt(6)
	ds_write2_b32 v3, v28, v29 offset1:1
	ds_write2_b32 v5, v30, v31 offset1:1
	s_waitcnt vmcnt(5)
	ds_write2_b32 v11, v36, v37 offset1:1
	ds_write2_b32 v12, v38, v39 offset1:1
	s_waitcnt vmcnt(4)
	ds_write2_b32 v13, v40, v41 offset1:1
	ds_write2_b32 v14, v42, v43 offset1:1
	s_waitcnt vmcnt(3)
	ds_write2_b32 v15, v44, v45 offset1:1
	ds_write2_b32 v16, v46, v47 offset1:1
	s_waitcnt vmcnt(2)
	ds_write2_b32 v17, v48, v49 offset1:1
	ds_write2_b32 v18, v50, v51 offset1:1
	s_waitcnt vmcnt(1)
	ds_write2_b32 v19, v52, v53 offset1:1
	ds_write2_b32 v20, v54, v55 offset1:1
	s_waitcnt vmcnt(0)
	ds_write2_b32 v21, v56, v57 offset1:1
	ds_write2_b32 v22, v58, v59 offset1:1
	s_waitcnt lgkmcnt(0)
	ds_read2_b32 v[28:29], v1 offset0:33 offset1:41
	ds_read2_b32 v[30:31], v1 offset1:8
	ds_read2_b32 v[36:37], v1 offset0:66 offset1:74
	ds_read2_b32 v[38:39], v1 offset0:99 offset1:107
	ds_read2_b32 v[40:41], v1 offset0:132 offset1:140
	ds_read2_b32 v[42:43], v1 offset0:165 offset1:173
	ds_read2_b32 v[44:45], v1 offset0:198 offset1:206
	ds_read2_b32 v[46:47], v1 offset0:231 offset1:239
	ds_read2_b32 v[48:49], v1 offset0:49 offset1:57
	ds_read2_b32 v[50:51], v1 offset0:16 offset1:24
	ds_read2_b32 v[52:53], v1 offset0:82 offset1:90
	ds_read2_b32 v[54:55], v1 offset0:115 offset1:123
	ds_read2_b32 v[56:57], v1 offset0:148 offset1:156
	ds_read2_b32 v[58:59], v1 offset0:181 offset1:189
	ds_read2_b32 v[66:67], v1 offset0:214 offset1:222
	ds_read2_b32 v[68:69], v1 offset0:247 offset1:255
	s_waitcnt lgkmcnt(14)
	v_cvt_pk_bf16_f32 v24, v30, v28
	s_waitcnt lgkmcnt(12)
	v_cvt_pk_bf16_f32 v25, v36, v38
	s_waitcnt lgkmcnt(10)
	v_cvt_pk_bf16_f32 v26, v40, v42
	s_waitcnt lgkmcnt(8)
	v_cvt_pk_bf16_f32 v27, v44, v46
	v_cvt_pk_bf16_f32 v28, v31, v29
	v_cvt_pk_bf16_f32 v29, v37, v39
	v_cvt_pk_bf16_f32 v30, v41, v43
	v_cvt_pk_bf16_f32 v31, v45, v47
	s_waitcnt lgkmcnt(6)
	v_cvt_pk_bf16_f32 v36, v50, v48
	s_waitcnt lgkmcnt(4)
	v_cvt_pk_bf16_f32 v37, v52, v54
	s_waitcnt lgkmcnt(2)
	v_cvt_pk_bf16_f32 v38, v56, v58
	s_waitcnt lgkmcnt(0)
	v_cvt_pk_bf16_f32 v39, v66, v68
	v_cvt_pk_bf16_f32 v40, v51, v49
	v_cvt_pk_bf16_f32 v41, v53, v55
	v_cvt_pk_bf16_f32 v42, v57, v59
	v_cvt_pk_bf16_f32 v43, v67, v69
	global_store_dwordx4 v[60:61], v[24:27], off
	global_store_dwordx4 v[62:63], v[28:31], off
	global_store_dwordx4 v[64:65], v[36:39], off
	global_store_dwordx4 v[32:33], v[40:43], off
	s_waitcnt lgkmcnt(0)
	s_cbranch_scc1 .LBB0_49
	v_readlane_b32 s36, v250, 12
	v_lshlrev_b32_e32 v6, 2, v2
	v_mov_b32_e32 v7, 0
	v_readlane_b32 s48, v250, 24
	v_readlane_b32 s49, v250, 25
	v_readlane_b32 s0, v250, 28
	v_readlane_b32 s1, v250, 29
	v_lshl_add_u64 v[2:3], s[48:49], 0, v[6:7]
	v_lshlrev_b32_e32 v6, 1, v4
	v_lshl_add_u64 v[4:5], s[0:1], 0, v[6:7]
	s_mov_b32 s7, s34
	v_readlane_b32 s37, v250, 13
	v_readlane_b32 s38, v250, 14
	v_readlane_b32 s39, v250, 15
	v_readlane_b32 s40, v250, 16
	v_readlane_b32 s41, v250, 17
	v_readlane_b32 s42, v250, 18
	v_readlane_b32 s43, v250, 19
	v_readlane_b32 s44, v250, 20
	v_readlane_b32 s45, v250, 21
	v_readlane_b32 s46, v250, 22
	v_readlane_b32 s47, v250, 23
	v_readlane_b32 s50, v250, 26
	v_readlane_b32 s51, v250, 27
; #define LAS __attribute__((address_space(3)))
; __device__ __forceinline__ unsigned pkbf(float lo, float hi) { const f32x2_m v = {lo, hi}; const bf16x2_m b = __builtin_convertvector(v, bf16x2_m); return __builtin_bit_cast(unsigned, b); }
; __device__ __forceinline__ void tr_item(const float* W, const float* nw, int K, int N, bf16* WT, int k0, int n0, int drow0, LAS float* scr, int lane) {
;     { const int r = lane >> 3, c4 = lane & 7; f32x4 v[8];
; #pragma unroll
;       for (int i = 0; i < 8; ++i) v[i] = *(const f32x4*)(W + (size_t)(k0 + 8 * i + r) * N + n0 + 4 * c4);
; #pragma unroll
;       for (int i = 0; i < 8; ++i) { LAS float* d = scr + (8 * i + r) * 33 + 4 * c4; const float s = nw ? nw[k0 + 8 * i + r] : 1.f; d[0] = v[i].x * s; d[1] = v[i].y * s; d[2] = v[i].z * s; d[3] = v[i].w * s; } }
;     asm volatile("s_waitcnt lgkmcnt(0)" ::: "memory");
;     const int c = lane & 7;
; #pragma unroll
;     for (int j = 0; j < 4; ++j) { const int n = (lane >> 3) + 8 * j; const LAS float* s = scr + (8 * c) * 33 + n;
;         v4u o; o.x = pkbf(s[0 * 33], s[1 * 33]); o.y = pkbf(s[2 * 33], s[3 * 33]); o.z = pkbf(s[4 * 33], s[5 * 33]); o.w = pkbf(s[6 * 33], s[7 * 33]);
;         *(v4u*)(WT + (size_t)(drow0 + n) * K + k0 + 8 * c) = o; }
;     asm volatile("s_waitcnt lgkmcnt(0)" ::: "memory");
; }
; template <int MODE> __device__ __forceinline__ void conv_mat(const float* W, const float* nw, int K, int N, bf16* WT, LAS float* scr, int gw, int NGW, int lane) {
;     const int nblk = N / 32, nitems = (K / 64) * nblk;
;     for (int it = gw; it < nitems; it += NGW) { const int kb = it / nblk, nb = it % nblk, n0 = 32 * nb; int d = n0;
;         if (MODE == 1) { d = (n0 < DFF) ? 256 * (n0 / 128) + (n0 % 128) : 256 * ((n0 - DFF) / 128) + 128 + ((n0 - DFF) % 128); }
;         tr_item(W, nw, K, N, WT, 64 * kb, n0, d, scr, lane); }
.LBB0_51:
	s_ashr_i32 s0, s7, 31
	s_lshr_b32 s0, s0, 26
	s_add_i32 s0, s7, s0
	s_lshl_b32 s1, s0, 5
	s_andn2_b32 s0, s0, 63
	s_and_b32 s1, s1, 0xfffff800
	v_or_b32_e32 v6, s0, v224
	s_sub_i32 s4, s3, s1
	v_or_b32_e32 v8, 8, v6
	v_or_b32_e32 v12, 16, v6
	v_or_b32_e32 v14, 24, v6
	v_or_b32_e32 v18, 40, v6
	v_or_b32_e32 v20, 48, v6
	v_or_b32_e32 v22, 56, v6
	v_ashrrev_i32_e32 v7, 31, v6
	v_or_b32_e32 v16, 32, v6
	s_ashr_i32 s5, s4, 31
	v_ashrrev_i32_e32 v9, 31, v8
	v_ashrrev_i32_e32 v13, 31, v12
	v_ashrrev_i32_e32 v15, 31, v14
	v_ashrrev_i32_e32 v19, 31, v18
	v_ashrrev_i32_e32 v21, 31, v20
	v_ashrrev_i32_e32 v23, 31, v22
	v_lshlrev_b64 v[6:7], 13, v[6:7]
	v_ashrrev_i32_e32 v17, 31, v16
	v_lshl_add_u64 v[24:25], s[4:5], 2, v[2:3]
	v_lshlrev_b64 v[8:9], 13, v[8:9]
	v_lshlrev_b64 v[12:13], 13, v[12:13]
	v_lshlrev_b64 v[14:15], 13, v[14:15]
	v_lshlrev_b64 v[18:19], 13, v[18:19]
	v_lshlrev_b64 v[20:21], 13, v[20:21]
	v_lshlrev_b64 v[22:23], 13, v[22:23]
	v_lshlrev_b64 v[16:17], 13, v[16:17]
	v_lshl_add_u64 v[6:7], v[24:25], 0, v[6:7]
	v_lshl_add_u64 v[26:27], v[24:25], 0, v[8:9]
	v_lshl_add_u64 v[28:29], v[24:25], 0, v[12:13]
	v_lshl_add_u64 v[30:31], v[24:25], 0, v[14:15]
	v_lshl_add_u64 v[36:37], v[24:25], 0, v[18:19]
	v_lshl_add_u64 v[38:39], v[24:25], 0, v[20:21]
	v_lshl_add_u64 v[40:41], v[24:25], 0, v[22:23]
	v_lshl_add_u64 v[32:33], v[24:25], 0, v[16:17]
	global_load_dwordx4 v[6:9], v[6:7], off nt
	s_nop 0
	global_load_dwordx4 v[12:15], v[26:27], off nt
	global_load_dwordx4 v[16:19], v[28:29], off nt
	global_load_dwordx4 v[20:23], v[30:31], off nt
	s_nop 0
	global_load_dwordx4 v[24:27], v[32:33], off nt
	global_load_dwordx4 v[28:31], v[36:37], off nt
	s_nop 0
	global_load_dwordx4 v[36:39], v[38:39], off nt
	s_nop 0
	global_load_dwordx4 v[40:43], v[40:41], off nt
	v_add_u32_e32 v44, s4, v224
	v_add_u32_e32 v46, 8, v44
	v_add_u32_e32 v48, 16, v44
	v_add_u32_e32 v50, 24, v44
	v_add_u32_e32 v11, 0x420, v10
	v_add_u32_e32 v35, 0x428, v10
	v_add_u32_e32 v52, 0x840, v10
	v_add_u32_e32 v53, 0x848, v10
	v_add_u32_e32 v54, 0xc60, v10
	v_add_u32_e32 v55, 0xc68, v10
	v_add_u32_e32 v56, 0x1080, v10
	v_add_u32_e32 v57, 0x1088, v10
	v_add_u32_e32 v58, 0x14a0, v10
	v_add_u32_e32 v59, 0x14a8, v10
	v_add_u32_e32 v60, 0x18c0, v10
	v_add_u32_e32 v61, 0x18c8, v10
	v_add_u32_e32 v62, 0x1ce0, v10
	v_add_u32_e32 v63, 0x1ce8, v10
	s_ashr_i32 s1, s0, 31
	v_ashrrev_i32_e32 v45, 31, v44
	v_ashrrev_i32_e32 v47, 31, v46
	v_ashrrev_i32_e32 v49, 31, v48
	v_ashrrev_i32_e32 v51, 31, v50
	v_lshl_add_u64 v[32:33], s[0:1], 1, v[4:5]
	v_lshlrev_b64 v[44:45], 11, v[44:45]
	v_lshlrev_b64 v[46:47], 11, v[46:47]
	v_lshlrev_b64 v[48:49], 11, v[48:49]
	v_lshlrev_b64 v[50:51], 11, v[50:51]
	v_lshl_add_u64 v[44:45], v[32:33], 0, v[44:45]
	v_lshl_add_u64 v[46:47], v[32:33], 0, v[46:47]
	v_lshl_add_u64 v[48:49], v[32:33], 0, v[48:49]
	v_lshl_add_u64 v[32:33], v[32:33], 0, v[50:51]
	s_add_i32 s7, s7, s64
	s_add_i32 s3, s3, s6
	s_cmpk_lt_i32 s7, 0x400
	s_waitcnt vmcnt(7)
	ds_write2_b32 v10, v6, v7 offset1:1
	ds_write2_b32 v10, v8, v9 offset0:2 offset1:3
	s_waitcnt vmcnt(6)
	ds_write2_b32 v11, v12, v13 offset1:1
	ds_write2_b32 v35, v14, v15 offset1:1
	s_waitcnt vmcnt(5)
	ds_write2_b32 v52, v16, v17 offset1:1
	ds_write2_b32 v53, v18, v19 offset1:1
	s_waitcnt vmcnt(4)
	ds_write2_b32 v54, v20, v21 offset1:1
	ds_write2_b32 v55, v22, v23 offset1:1
	s_waitcnt vmcnt(3)
	ds_write2_b32 v56, v24, v25 offset1:1
	ds_write2_b32 v57, v26, v27 offset1:1
	s_waitcnt vmcnt(2)
	ds_write2_b32 v58, v28, v29 offset1:1
	ds_write2_b32 v59, v30, v31 offset1:1
	s_waitcnt vmcnt(1)
	ds_write2_b32 v60, v36, v37 offset1:1
	ds_write2_b32 v61, v38, v39 offset1:1
	s_waitcnt vmcnt(0)
	ds_write2_b32 v62, v40, v41 offset1:1
	ds_write2_b32 v63, v42, v43 offset1:1
	s_waitcnt lgkmcnt(0)
	ds_read2_b32 v[12:13], v1 offset0:33 offset1:41
	ds_read2_b32 v[14:15], v1 offset1:8
	ds_read2_b32 v[16:17], v1 offset0:66 offset1:74
	ds_read2_b32 v[18:19], v1 offset0:99 offset1:107
	ds_read2_b32 v[20:21], v1 offset0:132 offset1:140
	ds_read2_b32 v[22:23], v1 offset0:165 offset1:173
	ds_read2_b32 v[24:25], v1 offset0:198 offset1:206
	ds_read2_b32 v[26:27], v1 offset0:231 offset1:239
	ds_read2_b32 v[28:29], v1 offset0:49 offset1:57
	ds_read2_b32 v[30:31], v1 offset0:16 offset1:24
	ds_read2_b32 v[36:37], v1 offset0:82 offset1:90
	ds_read2_b32 v[38:39], v1 offset0:115 offset1:123
	ds_read2_b32 v[40:41], v1 offset0:148 offset1:156
	ds_read2_b32 v[42:43], v1 offset0:181 offset1:189
	ds_read2_b32 v[50:51], v1 offset0:214 offset1:222
	ds_read2_b32 v[52:53], v1 offset0:247 offset1:255
	s_waitcnt lgkmcnt(14)
	v_cvt_pk_bf16_f32 v6, v14, v12
	s_waitcnt lgkmcnt(12)
	v_cvt_pk_bf16_f32 v7, v16, v18
	s_waitcnt lgkmcnt(10)
	v_cvt_pk_bf16_f32 v8, v20, v22
	s_waitcnt lgkmcnt(8)
	v_cvt_pk_bf16_f32 v9, v24, v26
	v_cvt_pk_bf16_f32 v12, v15, v13
	v_cvt_pk_bf16_f32 v13, v17, v19
	v_cvt_pk_bf16_f32 v14, v21, v23
	v_cvt_pk_bf16_f32 v15, v25, v27
	s_waitcnt lgkmcnt(6)
	v_cvt_pk_bf16_f32 v16, v30, v28
	s_waitcnt lgkmcnt(4)
	v_cvt_pk_bf16_f32 v17, v36, v38
	s_waitcnt lgkmcnt(2)
	v_cvt_pk_bf16_f32 v18, v40, v42
	s_waitcnt lgkmcnt(0)
	v_cvt_pk_bf16_f32 v19, v50, v52
	v_cvt_pk_bf16_f32 v20, v31, v29
	v_cvt_pk_bf16_f32 v21, v37, v39
	v_cvt_pk_bf16_f32 v22, v41, v43
	v_cvt_pk_bf16_f32 v23, v51, v53
	global_store_dwordx4 v[44:45], v[6:9], off
	global_store_dwordx4 v[46:47], v[12:15], off
	global_store_dwordx4 v[48:49], v[16:19], off
	global_store_dwordx4 v[32:33], v[20:23], off
	s_waitcnt lgkmcnt(0)
	s_cbranch_scc1 .LBB0_51

; #define LAS __attribute__((address_space(3)))
; __device__ __forceinline__ unsigned pkbf(float lo, float hi) { const f32x2_m v = {lo, hi}; const bf16x2_m b = __builtin_convertvector(v, bf16x2_m); return __builtin_bit_cast(unsigned, b); }
; __device__ __forceinline__ void tr_item(const float* W, const float* nw, int K, int N, bf16* WT, int k0, int n0, int drow0, LAS float* scr, int lane) {
;     { const int r = lane >> 3, c4 = lane & 7; f32x4 v[8];
; #pragma unroll
;       for (int i = 0; i < 8; ++i) v[i] = *(const f32x4*)(W + (size_t)(k0 + 8 * i + r) * N + n0 + 4 * c4);
; #pragma unroll
;       for (int i = 0; i < 8; ++i) { LAS float* d = scr + (8 * i + r) * 33 + 4 * c4; const float s = nw ? nw[k0 + 8 * i + r] : 1.f; d[0] = v[i].x * s; d[1] = v[i].y * s; d[2] = v[i].z * s; d[3] = v[i].w * s; } }
;     asm volatile("s_waitcnt lgkmcnt(0)" ::: "memory");
;     const int c = lane & 7;
; #pragma unroll
;     for (int j = 0; j < 4; ++j) { const int n = (lane >> 3) + 8 * j; const LAS float* s = scr + (8 * c) * 33 + n;
;         v4u o; o.x = pkbf(s[0 * 33], s[1 * 33]); o.y = pkbf(s[2 * 33], s[3 * 33]); o.z = pkbf(s[4 * 33], s[5 * 33]); o.w = pkbf(s[6 * 33], s[7 * 33]);
;         *(v4u*)(WT + (size_t)(drow0 + n) * K + k0 + 8 * c) = o; }
;     asm volatile("s_waitcnt lgkmcnt(0)" ::: "memory");
; }
; template <int MODE> __device__ __forceinline__ void conv_mat(const float* W, const float* nw, int K, int N, bf16* WT, LAS float* scr, int gw, int NGW, int lane) {
;     const int nblk = N / 32, nitems = (K / 64) * nblk;
;     for (int it = gw; it < nitems; it += NGW) { const int kb = it / nblk, nb = it % nblk, n0 = 32 * nb; int d = n0;
;         if (MODE == 1) { d = (n0 < DFF) ? 256 * (n0 / 128) + (n0 % 128) : 256 * ((n0 - DFF) / 128) + 128 + ((n0 - DFF) % 128); }
;         tr_item(W, nw, K, N, WT, 64 * kb, n0, d, scr, lane); }
.LBB0_54:
	s_ashr_i32 s0, s7, 31
	s_lshr_b32 s0, s0, 26
	s_add_i32 s0, s7, s0
	s_lshl_b32 s1, s0, 5
	s_andn2_b32 s0, s0, 63
	s_and_b32 s1, s1, 0xfffff800
	v_or_b32_e32 v22, s0, v224
	s_sub_i32 s4, s3, s1
	v_or_b32_e32 v24, 8, v22
	v_or_b32_e32 v26, 16, v22
	v_or_b32_e32 v28, 24, v22
	v_or_b32_e32 v30, 32, v22
	v_or_b32_e32 v32, 40, v22
	v_or_b32_e32 v36, 48, v22
	v_or_b32_e32 v38, 56, v22
	v_ashrrev_i32_e32 v23, 31, v22
	s_ashr_i32 s5, s4, 31
	v_ashrrev_i32_e32 v25, 31, v24
	v_ashrrev_i32_e32 v27, 31, v26
	v_ashrrev_i32_e32 v29, 31, v28
	v_ashrrev_i32_e32 v31, 31, v30
	v_ashrrev_i32_e32 v33, 31, v32
	v_ashrrev_i32_e32 v37, 31, v36
	v_ashrrev_i32_e32 v39, 31, v38
	v_lshlrev_b64 v[22:23], 13, v[22:23]
	v_lshl_add_u64 v[40:41], s[4:5], 2, v[2:3]
	v_lshlrev_b64 v[24:25], 13, v[24:25]
	v_lshlrev_b64 v[26:27], 13, v[26:27]
	v_lshlrev_b64 v[28:29], 13, v[28:29]
	v_lshlrev_b64 v[30:31], 13, v[30:31]
	v_lshlrev_b64 v[32:33], 13, v[32:33]
	v_lshlrev_b64 v[36:37], 13, v[36:37]
	v_lshlrev_b64 v[38:39], 13, v[38:39]
	v_lshl_add_u64 v[22:23], v[40:41], 0, v[22:23]
	v_lshl_add_u64 v[42:43], v[40:41], 0, v[24:25]
	v_lshl_add_u64 v[44:45], v[40:41], 0, v[26:27]
	v_lshl_add_u64 v[46:47], v[40:41], 0, v[28:29]
	v_lshl_add_u64 v[48:49], v[40:41], 0, v[30:31]
	v_lshl_add_u64 v[50:51], v[40:41], 0, v[32:33]
	v_lshl_add_u64 v[52:53], v[40:41], 0, v[36:37]
	v_lshl_add_u64 v[54:55], v[40:41], 0, v[38:39]
	global_load_dwordx4 v[22:25], v[22:23], off nt
	s_nop 0
	global_load_dwordx4 v[26:29], v[42:43], off nt
	global_load_dwordx4 v[30:33], v[44:45], off nt
	global_load_dwordx4 v[36:39], v[46:47], off nt
	s_nop 0
	global_load_dwordx4 v[40:43], v[48:49], off nt
	global_load_dwordx4 v[44:47], v[50:51], off nt
	s_nop 0
	global_load_dwordx4 v[48:51], v[52:53], off nt
	s_nop 0
	global_load_dwordx4 v[52:55], v[54:55], off nt
	v_add_u32_e32 v58, s4, v224
	v_add_u32_e32 v60, 8, v58
	v_add_u32_e32 v62, 16, v58
	v_add_u32_e32 v64, 24, v58
	s_ashr_i32 s1, s0, 31
	v_ashrrev_i32_e32 v59, 31, v58
	v_ashrrev_i32_e32 v61, 31, v60
	v_ashrrev_i32_e32 v63, 31, v62
	v_ashrrev_i32_e32 v65, 31, v64
	v_lshl_add_u64 v[56:57], s[0:1], 1, v[4:5]
	v_lshlrev_b64 v[58:59], 12, v[58:59]
	v_lshlrev_b64 v[60:61], 12, v[60:61]
	v_lshlrev_b64 v[62:63], 12, v[62:63]
	v_lshlrev_b64 v[64:65], 12, v[64:65]
	v_lshl_add_u64 v[58:59], v[56:57], 0, v[58:59]
	v_lshl_add_u64 v[60:61], v[56:57], 0, v[60:61]
	v_lshl_add_u64 v[62:63], v[56:57], 0, v[62:63]
	v_lshl_add_u64 v[56:57], v[56:57], 0, v[64:65]
	s_add_i32 s7, s7, s64
	s_add_i32 s3, s3, s6
	s_cmpk_lt_i32 s7, 0x800
	s_waitcnt vmcnt(7)
	ds_write2_b32 v6, v22, v23 offset1:1
	ds_write2_b32 v6, v24, v25 offset0:2 offset1:3
	s_waitcnt vmcnt(6)
	ds_write2_b32 v7, v26, v27 offset1:1
	ds_write2_b32 v8, v28, v29 offset1:1
	s_waitcnt vmcnt(5)
	ds_write2_b32 v9, v30, v31 offset1:1
	ds_write2_b32 v10, v32, v33 offset1:1
	s_waitcnt vmcnt(4)
	ds_write2_b32 v11, v36, v37 offset1:1
	ds_write2_b32 v12, v38, v39 offset1:1
	s_waitcnt vmcnt(3)
	ds_write2_b32 v13, v40, v41 offset1:1
	ds_write2_b32 v14, v42, v43 offset1:1
	s_waitcnt vmcnt(2)
	ds_write2_b32 v15, v44, v45 offset1:1
	ds_write2_b32 v16, v46, v47 offset1:1
	s_waitcnt vmcnt(1)
	ds_write2_b32 v17, v48, v49 offset1:1
	ds_write2_b32 v18, v50, v51 offset1:1
	s_waitcnt vmcnt(0)
	ds_write2_b32 v19, v52, v53 offset1:1
	ds_write2_b32 v20, v54, v55 offset1:1
	s_waitcnt lgkmcnt(0)
	ds_read2_b32 v[26:27], v1 offset0:33 offset1:41
	ds_read2_b32 v[28:29], v1 offset1:8
	ds_read2_b32 v[30:31], v1 offset0:66 offset1:74
	ds_read2_b32 v[32:33], v1 offset0:99 offset1:107
	ds_read2_b32 v[36:37], v1 offset0:132 offset1:140
	ds_read2_b32 v[38:39], v1 offset0:165 offset1:173
	ds_read2_b32 v[40:41], v1 offset0:198 offset1:206
	ds_read2_b32 v[42:43], v1 offset0:231 offset1:239
	ds_read2_b32 v[44:45], v1 offset0:49 offset1:57
	ds_read2_b32 v[46:47], v1 offset0:16 offset1:24
	ds_read2_b32 v[48:49], v1 offset0:82 offset1:90
	ds_read2_b32 v[50:51], v1 offset0:115 offset1:123
	ds_read2_b32 v[52:53], v1 offset0:148 offset1:156
	ds_read2_b32 v[54:55], v1 offset0:181 offset1:189
	ds_read2_b32 v[64:65], v1 offset0:214 offset1:222
	ds_read2_b32 v[66:67], v1 offset0:247 offset1:255
	s_waitcnt lgkmcnt(14)
	v_cvt_pk_bf16_f32 v22, v28, v26
	s_waitcnt lgkmcnt(12)
	v_cvt_pk_bf16_f32 v23, v30, v32
	s_waitcnt lgkmcnt(10)
	v_cvt_pk_bf16_f32 v24, v36, v38
	s_waitcnt lgkmcnt(8)
	v_cvt_pk_bf16_f32 v25, v40, v42
	v_cvt_pk_bf16_f32 v26, v29, v27
	v_cvt_pk_bf16_f32 v27, v31, v33
	v_cvt_pk_bf16_f32 v28, v37, v39
	v_cvt_pk_bf16_f32 v29, v41, v43
	s_waitcnt lgkmcnt(6)
	v_cvt_pk_bf16_f32 v30, v46, v44
	s_waitcnt lgkmcnt(4)
	v_cvt_pk_bf16_f32 v31, v48, v50
	s_waitcnt lgkmcnt(2)
	v_cvt_pk_bf16_f32 v32, v52, v54
	s_waitcnt lgkmcnt(0)
	v_cvt_pk_bf16_f32 v33, v64, v66
	v_cvt_pk_bf16_f32 v36, v47, v45
	v_cvt_pk_bf16_f32 v37, v49, v51
	v_cvt_pk_bf16_f32 v38, v53, v55
	v_cvt_pk_bf16_f32 v39, v65, v67
	global_store_dwordx4 v[58:59], v[22:25], off
	global_store_dwordx4 v[60:61], v[26:29], off
	global_store_dwordx4 v[62:63], v[30:33], off
	global_store_dwordx4 v[56:57], v[36:39], off
	s_waitcnt lgkmcnt(0)
	s_cbranch_scc1 .LBB0_54

; __device__ __forceinline__ void prep_rows_bf16(const float* X, float* rs, bf16* Hout, int gw, int NGW, int lane) {
;     for (int m = gw; m < M; m += NGW) { const f32x4* xr = (const f32x4*)(X + (size_t)m * DM) + lane; f32x4 v[8]; float s = 0.f;
; #pragma unroll
;         for (int j = 0; j < 8; ++j) { v[j] = xr[64 * j]; s += (v[j].x * v[j].x + v[j].y * v[j].y) + (v[j].z * v[j].z + v[j].w * v[j].w); }
;         const float rstd = 1.0f / sqrtf(wave_sum(s) * (1.f / DM) + EPS);
;         if (lane == 0) rs[m] = rstd;
;         v2u* o = (v2u*)(Hout + (size_t)m * DM) + lane;
.LBB0_69:
	global_load_dwordx4 v[6:9], v[36:37], off offset:-4096 nt
	global_load_dwordx4 v[2:5], v[36:37], off offset:-3072 nt
	global_load_dwordx4 v[10:13], v[36:37], off offset:-2048 nt
	global_load_dwordx4 v[14:17], v[36:37], off offset:-1024 nt
	global_load_dwordx4 v[18:21], v[36:37], off nt
	global_load_dwordx4 v[22:25], v[36:37], off offset:1024 nt
	global_load_dwordx4 v[26:29], v[36:37], off offset:2048 nt
	global_load_dwordx4 v[30:33], v[36:37], off offset:3072 nt
	s_waitcnt vmcnt(7)
	v_mul_f32_e32 v46, v7, v7
	v_mul_f32_e32 v47, v9, v9
	s_waitcnt vmcnt(6)
	v_mul_f32_e32 v48, v3, v3
	v_mul_f32_e32 v49, v5, v5
	s_waitcnt vmcnt(5)
	v_mul_f32_e32 v50, v11, v11
	v_mul_f32_e32 v51, v13, v13
	v_fmac_f32_e32 v46, v6, v6
	v_fmac_f32_e32 v47, v8, v8
	v_fmac_f32_e32 v48, v2, v2
	v_fmac_f32_e32 v49, v4, v4
	s_waitcnt vmcnt(4)
	v_mul_f32_e32 v52, v15, v15
	v_mul_f32_e32 v53, v17, v17
	v_fmac_f32_e32 v50, v10, v10
	v_fmac_f32_e32 v51, v12, v12
	v_add_f32_e32 v46, v46, v47
	v_add_f32_e32 v47, v48, v49
	s_waitcnt vmcnt(3)
	v_mul_f32_e32 v54, v19, v19
	v_mul_f32_e32 v55, v21, v21
	v_fmac_f32_e32 v52, v14, v14
	v_fmac_f32_e32 v53, v16, v16
	v_add_f32_e32 v48, v50, v51
	v_add_f32_e32 v46, v46, v47
	s_waitcnt vmcnt(2)
	v_mul_f32_e32 v56, v23, v23
	v_mul_f32_e32 v57, v25, v25
	v_fmac_f32_e32 v54, v18, v18
	v_fmac_f32_e32 v55, v20, v20
	v_add_f32_e32 v49, v52, v53
	v_add_f32_e32 v46, v46, v48
	s_waitcnt vmcnt(1)
	v_mul_f32_e32 v58, v27, v27
	v_mul_f32_e32 v59, v29, v29
	v_fmac_f32_e32 v56, v22, v22
	v_fmac_f32_e32 v57, v24, v24
	v_add_f32_e32 v50, v54, v55
	v_add_f32_e32 v46, v46, v49
	s_waitcnt vmcnt(0)
	v_mul_f32_e32 v60, v31, v31
	v_mul_f32_e32 v61, v33, v33
	v_fmac_f32_e32 v58, v26, v26
	v_fmac_f32_e32 v59, v28, v28
	v_add_f32_e32 v51, v56, v57
	v_add_f32_e32 v46, v46, v50
	v_fmac_f32_e32 v60, v30, v30
	v_fmac_f32_e32 v61, v32, v32
	v_add_f32_e32 v52, v58, v59
	v_add_f32_e32 v46, v46, v51
	v_add_f32_e32 v46, v46, v52
	v_add_f32_e32 v47, v60, v61
	v_add_f32_e32 v46, v46, v47
	ds_bpermute_b32 v47, v1, v46
	s_waitcnt lgkmcnt(0)
	v_add_f32_e32 v46, v46, v47
	ds_bpermute_b32 v47, v40, v46
	s_waitcnt lgkmcnt(0)
	v_add_f32_e32 v46, v46, v47
	ds_bpermute_b32 v47, v41, v46
	s_waitcnt lgkmcnt(0)
	v_add_f32_e32 v46, v46, v47
	ds_bpermute_b32 v47, v42, v46
	s_waitcnt lgkmcnt(0)
	v_add_f32_e32 v46, v46, v47
	ds_bpermute_b32 v47, v43, v46
	s_waitcnt lgkmcnt(0)
	v_add_f32_e32 v46, v46, v47
	ds_bpermute_b32 v47, v44, v46
	s_and_saveexec_b64 s[14:15], s[0:1]
	s_cbranch_execz .LBB0_68
	s_waitcnt lgkmcnt(0)
	v_add_f32_e32 v46, v46, v47
	v_fmamk_f32 v46, v46, 0x3a000000, v34
	v_mul_f32_e32 v47, 0x4f800000, v46
	v_cmp_gt_f32_e32 vcc, s21, v46
	s_nop 1
	v_cndmask_b32_e32 v46, v46, v47, vcc
	v_sqrt_f32_e32 v47, v46
	s_nop 0
	v_add_u32_e32 v48, -1, v47
	v_fma_f32 v50, -v48, v47, v46
	v_add_u32_e32 v49, 1, v47
	v_cmp_ge_f32_e64 s[6:7], 0, v50
	s_nop 1
	v_cndmask_b32_e64 v48, v47, v48, s[6:7]
	v_fma_f32 v47, -v49, v47, v46
	v_cmp_lt_f32_e64 s[6:7], 0, v47
	s_nop 1
	v_cndmask_b32_e64 v47, v48, v49, s[6:7]
	v_mul_f32_e32 v48, 0x37800000, v47
	v_cndmask_b32_e32 v47, v47, v48, vcc
	v_cmp_class_f32_e32 vcc, v46, v45
	s_nop 1
	v_cndmask_b32_e32 v46, v47, v46, vcc
	v_div_scale_f32 v47, s[6:7], v46, v46, 1.0
	v_rcp_f32_e32 v48, v47
	s_add_u32 s6, s62, s3
	s_addc_u32 s7, s63, s20
	v_fma_f32 v49, -v47, v48, 1.0
	v_fmac_f32_e32 v48, v49, v48
	v_div_scale_f32 v49, vcc, 1.0, v46, 1.0
	v_mul_f32_e32 v50, v49, v48
	v_fma_f32 v51, -v47, v50, v49
	v_fmac_f32_e32 v50, v51, v48
	v_fma_f32 v47, -v47, v50, v49
	v_div_fmas_f32 v47, v47, v48, v50
	v_div_fixup_f32 v46, v47, v46, 1.0
	global_store_dword v35, v46, s[6:7]
	s_branch .LBB0_68
